# attention: next-pair LDS-DMA issue moved behind the first QK MFMA cluster (fills the MFMA-to-softmax dependency gap)
# speedup vs baseline: 1.0199x; 1.0009x over previous
; #define ALOAD(kt) { const int key0_ = (kt) * 128; \
;     if (kc < 12) { _Pragma("unroll") for (int i = 0; i < 4; ++i) kr[i] = *(const u32x4*)(Kb + (size_t)(key0_ + krow + 32 * i) * 96 + kc * 8); } \
;     _Pragma("unroll") for (int i = 0; i < 2; ++i) vr[i] = *(const u32x4*)(Vt + (size_t)vrow * NKEY + key0_ + i * 64 + vc * 8); }
; #define ASTORE(slot) { char* sk_ = smem + (slot) * KB; char* sv_ = smem + (slot) * VB; \
;     if (kc < 12) { _Pragma("unroll") for (int i = 0; i < 4; ++i) *(u32x4*)(sk_ + kwo + i * 8192) = kr[i]; } \
;     _Pragma("unroll") for (int i = 0; i < 2; ++i) *(u32x4*)(sv_ + vwo + i * VB) = vr[i]; }
; #define PVLOAD(slot) { const char* s = smem + (slot) * VB; \
;     _Pragma("unroll") for (int vt = 0; vt < 4; ++vt) vf[0][vt] = *(const bf16x8*)(s + vt * 2048 + vro + (((0 * 4 + lq) ^ (l15 >> 1)) << 4)); }
; DEV void attn_item(const P& p, int bh, int qrow0, int nkt, int outrow0, char* smem) {
;     ...
;   for (int kp = 0; kp < npair; ++kp) {
;     const int sn = (s0 == 4) ? 0 : s0 + 2;
;     if (kp + 1 < npair) ASTORE(sn);
;     if (kp + 2 < npair) ALOAD(kp + 2);
;     if (!skew) {
;       QK(s0); PVLOAD(s0); __builtin_amdgcn_sched_barrier(0); SM(kp == 0); PVMMA(s0);
.Latt_loop:
	s_add_i32 s2, s10, 2
	s_cmp_lg_u32 s10, 4
	s_cselect_b32 s24, s2, 0
	s_add_i32 s26, s11, 1
	v_lshl_add_u32 v8, s10, 14, v214
	v_add_u32_e32 v38, v8, v217
	v_add_u32_e32 v39, v8, v218
	v_add_u32_e32 v40, v8, v219
	s_lshl_b32 s27, s10, 13
	ds_read_b128 v[156:159], v38 offset:0
	ds_read_b128 v[160:163], v38 offset:4096
	ds_read_b128 v[164:167], v38 offset:8192
	ds_read_b128 v[168:171], v38 offset:12288
	ds_read_b128 v[172:175], v39 offset:0
	ds_read_b128 v[176:179], v39 offset:4096
	ds_read_b128 v[180:183], v39 offset:8192
	ds_read_b128 v[184:187], v39 offset:12288
	s_setprio 1
	s_waitcnt lgkmcnt(7)
	v_mfma_f32_16x16x32_bf16 v[140:143], v[156:159], v[44:47], v[226:229]
	v_mfma_f32_16x16x32_bf16 v[124:127], v[156:159], v[56:59], v[230:233]
	s_waitcnt lgkmcnt(6)
	v_mfma_f32_16x16x32_bf16 v[144:147], v[160:163], v[44:47], v[226:229]
	v_mfma_f32_16x16x32_bf16 v[128:131], v[160:163], v[56:59], v[230:233]
	s_waitcnt lgkmcnt(5)
	v_mfma_f32_16x16x32_bf16 v[148:151], v[164:167], v[44:47], v[226:229]
	v_mfma_f32_16x16x32_bf16 v[132:135], v[164:167], v[56:59], v[230:233]
	s_waitcnt lgkmcnt(4)
	v_mfma_f32_16x16x32_bf16 v[152:155], v[168:171], v[44:47], v[226:229]
	v_mfma_f32_16x16x32_bf16 v[136:139], v[168:171], v[56:59], v[230:233]
	s_waitcnt lgkmcnt(3)
	v_mfma_f32_16x16x32_bf16 v[140:143], v[172:175], v[48:51], v[140:143]
	v_mfma_f32_16x16x32_bf16 v[124:127], v[172:175], v[60:63], v[124:127]
	ds_read_b128 v[156:159], v40 offset:0
	ds_read_b128 v[160:163], v40 offset:4096
	ds_read_b128 v[164:167], v40 offset:8192
	ds_read_b128 v[168:171], v40 offset:12288
	s_waitcnt lgkmcnt(6)
	v_mfma_f32_16x16x32_bf16 v[144:147], v[176:179], v[48:51], v[144:147]
	v_mfma_f32_16x16x32_bf16 v[128:131], v[176:179], v[60:63], v[128:131]
	s_waitcnt lgkmcnt(5)
	v_mfma_f32_16x16x32_bf16 v[148:151], v[180:183], v[48:51], v[148:151]
	v_mfma_f32_16x16x32_bf16 v[132:135], v[180:183], v[60:63], v[132:135]
	s_waitcnt lgkmcnt(4)
	v_mfma_f32_16x16x32_bf16 v[152:155], v[184:187], v[48:51], v[152:155]
	v_mfma_f32_16x16x32_bf16 v[136:139], v[184:187], v[60:63], v[136:139]
	s_waitcnt lgkmcnt(3)
	v_mfma_f32_16x16x32_bf16 v[140:143], v[156:159], v[52:55], v[140:143]
	v_mfma_f32_16x16x32_bf16 v[124:127], v[156:159], v[64:67], v[124:127]
	s_waitcnt lgkmcnt(2)
	v_mfma_f32_16x16x32_bf16 v[144:147], v[160:163], v[52:55], v[144:147]
	v_mfma_f32_16x16x32_bf16 v[128:131], v[160:163], v[64:67], v[128:131]
	s_waitcnt lgkmcnt(1)
	v_mfma_f32_16x16x32_bf16 v[148:151], v[164:167], v[52:55], v[148:151]
	v_mfma_f32_16x16x32_bf16 v[132:135], v[164:167], v[64:67], v[132:135]
	s_waitcnt lgkmcnt(0)
	v_mfma_f32_16x16x32_bf16 v[152:155], v[168:171], v[52:55], v[152:155]
	v_mfma_f32_16x16x32_bf16 v[136:139], v[168:171], v[64:67], v[136:139]
	s_setprio 0
	s_add_i32 s2, s11, 2
	s_cmp_ge_i32 s2, s23
	s_cbranch_scc1 .Latt_nodma
	s_add_i32 s2, s24, 2
	s_cmp_lg_u32 s24, 4
	s_cselect_b32 s2, s2, 0
	s_lshl_b32 s3, s2, 14
	s_add_i32 s3, s3, s40
	s_add_i32 m0, s3, 0x0
	s_nop 0
	global_load_lds_dwordx4 v13, s[6:7]
	s_add_i32 m0, s3, 0x400
	s_nop 0
	global_load_lds_dwordx4 v14, s[6:7]
	s_add_i32 m0, s3, 0x800
	s_nop 0
	global_load_lds_dwordx4 v15, s[6:7]
	s_add_i32 m0, s3, 0xc00
	s_nop 0
	global_load_lds_dwordx4 v12, s[6:7]
	s_lshl_b32 s3, s2, 13
	s_add_i32 s3, s3, s41
	s_add_i32 s3, s3, 0x18000
	v_add_u32_e32 v9, 0x80, v234
	s_mov_b32 m0, s3
	s_nop 0
	global_load_lds_dwordx4 v234, s[8:9]
	s_add_i32 m0, s3, 0x2000
	s_nop 0
	global_load_lds_dwordx4 v9, s[8:9]
	s_add_u32 s6, s6, 0x6000
	s_addc_u32 s7, s7, 0
	s_add_u32 s8, s8, 0x100
	s_addc_u32 s9, s9, 0
.Latt_nodma:
	v_add_u32_e32 v8, s27, v210
	v_add_u32_e32 v42, v8, v215
	v_add_u32_e32 v43, v8, v216
	v_max3_f32 v36, v140, v141, v142
	v_max3_f32 v37, v124, v125, v126
	v_max3_f32 v36, v36, v143, v144
	v_max3_f32 v37, v37, v127, v128
	v_max3_f32 v36, v36, v145, v146
	v_max3_f32 v37, v37, v129, v130
	v_max3_f32 v36, v36, v147, v148
	v_max3_f32 v37, v37, v131, v132
	v_max3_f32 v36, v36, v149, v150
	v_max3_f32 v37, v37, v133, v134
	v_max3_f32 v36, v36, v151, v152
	v_max3_f32 v37, v37, v135, v136
	v_max3_f32 v36, v36, v153, v154
	v_max3_f32 v37, v37, v137, v138
	v_max3_f32 v36, v36, v155, v155
	v_max3_f32 v37, v37, v139, v139
	v_max_f32_e32 v9, v36, v37
	v_cmp_lt_f32_e32 vcc, s44, v9
	ds_read_b128 v[16:19], v42 offset:0
	ds_read_b128 v[20:23], v42 offset:2048
	ds_read_b128 v[24:27], v42 offset:4096
	ds_read_b128 v[28:31], v42 offset:6144
	ds_read_b128 v[188:191], v43 offset:0
	ds_read_b128 v[192:195], v43 offset:2048
	ds_read_b128 v[196:199], v43 offset:4096
	ds_read_b128 v[32:35], v43 offset:6144
	s_cmp_eq_u32 s11, 0
	s_cbranch_scc1 .Latt_rare_a
	s_cbranch_vccnz .Latt_rare_a
